# work-queue loops: next-item atomicAdd returns into the carried register (no immediate vmcnt(0)+readfirstlane at unit head); drop per-unit store-drain vmcnt(0) in P4 tail
# baseline (speedup 1.0000x reference)
; #define PG8_LAS __attribute__((address_space(3)))
; __device__ __forceinline__ int wg_tid(PG8_LAS unsigned char* ldsbase) {
;     const unsigned hw = (unsigned)__builtin_amdgcn_s_getreg((5 << 11) | 4) & 63u;
;     const unsigned wv = ((volatile PG8_LAS unsigned*)(ldsbase + WMAP_OFF))[hw];
;     const int lane = (int)__builtin_amdgcn_mbcnt_hi(~0u, __builtin_amdgcn_mbcnt_lo(~0u, 0u));
;     int t = (int)__builtin_amdgcn_readfirstlane(wv) * 64 + lane;
;     asm volatile("" : "+v"(t));
;     return t;
; __global__ void __launch_bounds__(512, 2) fwd_megakernel(Ptrs Parg) {
;     ...
;           while (it < 28 * NCH) { const int t2 = pg8::wg_tid(glds);
;               if (t2 == 0) nxt = atomicAdd(qctr, 1u);
.LBB0_299:
	s_getreg_b32 s3, hwreg(HW_REG_HW_ID, 0, 6)
	s_and_b32 s3, s3, 63
	s_lshl_b32 s3, s3, 2
	s_add_i32 s3, s3, 0
	s_add_i32 s3, s3, 0x27ef0
	v_mov_b32_e32 v10, s3
	ds_read_b32 v10, v10
	s_waitcnt lgkmcnt(0)
	v_readfirstlane_b32 s3, v10
	s_nop 1
	v_lshl_add_u32 v98, s3, 6, v213
	s_nop 0
	v_cmp_eq_u32_e64 s[36:37], 0, v98
	s_and_saveexec_b64 s[4:5], s[36:37]
	s_cbranch_execz .LBB0_303
	s_mov_b64 s[8:9], exec
	v_mbcnt_lo_u32_b32 v10, s8, 0
	v_mbcnt_hi_u32_b32 v10, s9, v10
	v_cmp_eq_u32_e32 vcc, 0, v10
	s_and_saveexec_b64 s[6:7], vcc
	s_cbranch_execz .LBB0_302
	s_bcnt1_i32_b64 s3, s[8:9]
	v_mov_b32_e32 v11, s3
	global_atomic_add v106, v[0:1], v11, off sc0
.LBB0_302:
	s_or_b64 exec, exec, s[6:7]
.LBB0_303:
	s_or_b64 exec, exec, s[4:5]
	s_mov_b64 s[4:5], -1
	s_cmpk_gt_i32 s74, 0x80f
	v_and_b32_e32 v108, 63, v98
	v_ashrrev_i32_e32 v107, 6, v98
	s_cbranch_scc1 .LBB0_306
	s_andn2_b64 vcc, exec, s[4:5]
	s_cbranch_vccz .LBB0_504

; __global__ void __launch_bounds__(512, 2) fwd_megakernel(Ptrs Parg) {
;     ...
;               if (t2 == 0) misc[2] = nxt;
;               __syncthreads();
;               it = (int)__builtin_amdgcn_readfirstlane(misc[2]); } }
.LBB0_612:
	v_readlane_b32 s3, v255, 22
	s_waitcnt vmcnt(0)
	v_mov_b32_e32 v10, s3
	ds_write_b32 v10, v106
	s_branch .LBB0_298

; __global__ void __launch_bounds__(512, 2) fwd_megakernel(Ptrs Parg) {
;     ...
;           while (it < 24 * NCH) { const int t2 = pg8::wg_tid(glds);
;               if (t2 == 0) nxt = atomicAdd(qctr, 1u);
;               if (it < 8 * NCH) { const int ch = it % NCH, bg = it / NCH; ssd_passB(P, l, bg >> 2, ch, bg & 3, lds, t2, true); }
;               else { const int i2 = it - 8 * NCH; const int ch = i2 % NCH, bh = i2 / NCH; hg_passB(P, l, bh >> 3, bh & 7, ch, lds, t2, true); }
;               if (t2 == 0) misc[2] = nxt;
;               __syncthreads();
;               it = (int)__builtin_amdgcn_readfirstlane(misc[2]); } }
.LBB0_765:
	s_or_b64 exec, exec, s[4:5]
	v_readlane_b32 s3, v255, 22
	s_waitcnt lgkmcnt(0)
	s_barrier
	s_nop 0
	v_mov_b32_e32 v8, s3
	ds_read_b32 v8, v8
	s_waitcnt lgkmcnt(0)
	v_readfirstlane_b32 s10, v8
	s_cmpk_gt_i32 s10, 0xc17
	s_cbranch_scc1 .LBB0_1079

; __global__ void __launch_bounds__(512, 2) fwd_megakernel(Ptrs Parg) {
;     ...
;               if (t2 == 0) nxt = atomicAdd(qctr, 1u);
.LBB0_770:
	s_mov_b64 s[8:9], exec
	v_mbcnt_lo_u32_b32 v8, s8, 0
	v_mbcnt_hi_u32_b32 v8, s9, v8
	v_cmp_eq_u32_e32 vcc, 0, v8
	s_and_saveexec_b64 s[6:7], vcc
	s_cbranch_execz .LBB0_772
	s_bcnt1_i32_b64 s3, s[8:9]
	v_mov_b32_e32 v9, s3
	global_atomic_add v210, v[158:159], v9, off sc0
.LBB0_772:
	s_or_b64 exec, exec, s[6:7]
	s_or_b64 exec, exec, s[4:5]
	s_cmpk_gt_i32 s10, 0x407
	s_mov_b64 s[4:5], -1
	s_cbranch_scc0 .LBB0_768
